# phase 4 overlapped again: d0 scan waves run at high priority, attention waves at priority 0 (attention is bandwidth-bound and needs few issue slots); serializing barrier removed
# speedup vs baseline: 1.0384x; 1.0068x over previous
; __device__ __forceinline__ void nat_phase(const Params& p, float* ldsf, int wave0, int nwaves) {
;     const int lane = threadIdx.x & 63, wid = __builtin_amdgcn_readfirstlane(threadIdx.x >> 6), l15 = lane & 15, lq = lane >> 4;
;     const u16* Qn = (const u16*)p.out; const u16* Kn = Qn + (size_t)NTOK * RW; const u16* VT = Kn + (size_t)NTOK * RW; const u16* Gn = VT + (size_t)NTOK * RW;
;     u16* MIX = (u16*)(p.ws + O_HN);
;     for (int item = wave0; item < 8192; item += nwaves) {
;         const int r = item & 255, h = (item >> 8) & 15, b = item >> 12;
;         const int rs = min(max(r - 4, 0), 248);
;         const u16* Qb = Qn + (size_t)(b * SEQ + r * 64) * RW + h * 64;
;         const u16* Kb = Kn + (size_t)(b * SEQ + rs * 64) * RW + h * 64;
;         const u16* Vb = VT + (size_t)((b * 16 + h) * 64) * SEQ + rs * 64;
;         float* tb = ldsf + wid * 256;
;         { const float* rpb = p.rpb + h * 465 + (rs - r + 7) * 31;
; #pragma unroll
;           for (int q = 0; q < 4; ++q) { const int e = lane + q * 64; if (e < 248) tb[e] = rpb[e]; } }
; template <bool MIX> __device__ __forceinline__ void scan_pass1(const Params& p, int d, float* ldsf) {
;     ...
;     if (MIX && wid >= 4) nat_phase(p, ldsf, blockIdx.x * 4 + (wid - 4), gridDim.x * 4);
.LBB0_413:
	s_cmp_lt_i32 s58, 5
	s_cselect_b64 s[0:1], -1, 0
	s_cmp_gt_i32 s59, 4
	s_cselect_b64 s[4:5], -1, 0
	s_and_b64 s[0:1], s[0:1], s[4:5]
	s_andn2_b64 vcc, exec, s[0:1]
	s_cbranch_vccnz .LBB0_628
	v_readfirstlane_b32 s0, v254
	v_and_b32_e32 v96, 63, v254
	s_cmpk_lt_u32 s0, 0x100
	v_and_b32_e32 v65, 15, v254
	s_cbranch_scc1 .LBB0_555
	s_setprio 0
	s_lshr_b32 s1, s0, 6
	s_lshl_b32 s88, s2, 2
	s_add_i32 s88, s88, s1
	s_add_i32 s88, s88, -4
	s_cmpk_gt_i32 s88, 0xfff
	s_cbranch_scc1 .Lmy_nat_end
	s_lshl_b32 s81, s96, 2
	s_mov_b32 s64, s56
	s_and_b32 s65, s57, 0xffff
	s_brev_b32 s66, -2
	s_mov_b32 s67, 0x27000
	s_mov_b32 s68, s54
	s_and_b32 s69, s55, 0xffff
	s_mov_b32 s70, s66
	s_mov_b32 s71, s67
	s_mov_b32 s72, s50
	s_and_b32 s73, s51, 0xffff
	s_movk_i32 s74, 0x7440
	s_mov_b32 s75, s67
	v_and_b32_e32 v237, 15, v254
	v_bfe_u32 v238, v254, 4, 2
	v_and_b32_e32 v242, 63, v254
	v_lshlrev_b32_e32 v243, 4, v238
	v_lshl_add_u32 v224, v237, 11, v243
	v_lshl_add_u32 v226, v237, 15, v243
	v_lshrrev_b32_e32 v244, 2, v237
	v_and_b32_e32 v245, 3, v237
	v_lshl_add_u32 v244, v244, 3, v245
	v_lshl_add_u32 v225, v244, 11, v243
	v_lshlrev_b32_e32 v243, 3, v238
	v_lshl_add_u32 v227, v237, 11, v243
	v_lshl_add_u32 v228, v237, 12, v243
	v_xor_b32_e32 v248, 16, v242
	v_lshlrev_b32_e32 v248, 2, v248
	v_xor_b32_e32 v249, 32, v242
	v_lshlrev_b32_e32 v249, 2, v249
	s_lshl_b32 s3, s1, 11
	s_add_u32 s3, s3, 0x6000
	v_lshl_add_u32 v250, v242, 2, s3
	v_mov_b32_e32 v243, 0xf2c9f2ca
	ds_write_b32 v250, v243 offset:1024
	ds_write_b32 v250, v243 offset:1280
	ds_write_b32 v250, v243 offset:1536
	ds_write_b32 v250, v243 offset:1792
	v_mov_b32_e32 v252, 0x3e38aa3b
	v_mov_b32_e32 v253, 0x3e38aa3b

; #define NEXT_ITEM() (MIX ? (int)__builtin_amdgcn_readfirstlane(lane == 0 ? __hip_atomic_fetch_add(qctr, 1u, __ATOMIC_RELAXED, __HIP_MEMORY_SCOPE_AGENT) : 0u) : item + (int)gridDim.x * 8)
; #define MKR(ptr) __builtin_amdgcn_make_buffer_rsrc((void*)(ptr), 0, 0x7fffffff, 0x00027000)
; template <bool MIX> __device__ __forceinline__ void scan_pass1(const Params& p, int d, float* ldsf) {
;     const int lane = threadIdx.x & 63, wid = __builtin_amdgcn_readfirstlane(threadIdx.x >> 6); const unsigned lo16 = (lane & 15) * 16, lo2 = lane * 2;
;     const float* Wd = (const float*)(p.ws + O_KD); const float* Bd = (const float*)(p.ws + O_Y); const u16* KB = (const u16*)(p.ws + O_K); const float* A = (const float*)(p.ws + O_A);
;     const u16* V = (const u16*)(p.ws + O_V); float* PT = (float*)(p.ws + O_PT); float* SLT = (float*)(p.ws + O_SLT); const unsigned lo8 = (lane & 15) * 8;
;     constexpr int NS = 32 * (NC - 1);
;     unsigned* qctr = (unsigned*)(p.ws + O_BAR);
;     if (MIX && wid >= 4) nat_phase(p, ldsf, blockIdx.x * 4 + (wid - 4), gridDim.x * 4);
;     ...
;     for (int item = MIX ? NEXT_ITEM() : (int)(blockIdx.x * 8 + wid); item < 2 * NS; item = NEXT_ITEM()) {
;         const bool isP = item >= NS; const int idx = isP ? item - NS : item;
;         const int bh = idx / (NC - 1), c = idx - bh * (NC - 1), b = bh >> 4, h = bh & 15;
;         const int t0 = d ? (SEQ - 1 - c * LC) : c * LC;
;         const size_t off0 = ((size_t)(b * SEQ + t0)) * RW + h * 64; const long stp = d ? -(long)RW : (long)RW;
;         const unsigned ob4 = (unsigned)(off0 * 4), ob2 = (unsigned)(off0 * 2);
;         const f32x4 ka4 = *(const f32x4*)(p.k_a + h * 64 + (lane & 15) * 4), c04 = 1.0f - ka4;
;         float S[64]; int ln = lane; asm volatile("" : "+v"(ln));
;     ...
;         const __amdgpu_buffer_rsrc_t rW = MKR(Wd), rA = MKR(A), rB = MKR(Bd), rK = MKR(KB), rV = MKR(V);
.Lmy_nat_end:
.LBB0_555:
	s_mov_b64 exec, -1
	s_setprio 3
	v_readfirstlane_b32 s0, v254
	s_nop 3
	s_lshr_b32 s1, s0, 6
	s_lshl_b32 s0, s2, 3
	s_add_i32 s0, s1, s0
	s_mov_b32 s64, s56
	s_and_b32 s65, s57, 0xffff
	s_brev_b32 s66, -2
	s_mov_b32 s67, 0x27000
	s_mov_b32 s68, s54
	s_and_b32 s69, s55, 0xffff
	s_mov_b32 s70, s66
	s_mov_b32 s71, s67
	v_and_b32_e32 v212, 63, v254
	v_and_b32_e32 v213, 15, v254
	v_lshlrev_b32_e32 v204, 4, v213
	v_lshlrev_b32_e32 v205, 3, v213
	v_lshlrev_b32_e32 v206, 1, v212
	v_lshlrev_b32_e32 v207, 2, v212
	v_lshlrev_b32_e32 v210, 8, v212
	s_lshl_b32 s3, s1, 10
	s_add_u32 s3, s3, 0x10000
	v_lshl_add_u32 v208, v213, 2, s3
	v_and_b32_e32 v209, 3, v254
	v_lshl_add_u32 v209, v209, 6, s3
	v_add_u32_e32 v232, 0xb800000, v204
	v_add_u32_e32 v233, 0x24800000, v204
	v_add_u32_e32 v234, 0x35a00000, v204
	v_add_u32_e32 v235, 0x1c800000, v204
	v_add_u32_e32 v236, 0x30800000, v205
	v_add_u32_e32 v237, 0x2c800000, v206
	v_mov_b32_e32 v213, 1.0
	v_mov_b32_e32 v214, 0
	v_mov_b32_e32 v215, 1
	s_mov_b64 exec, 1
	global_atomic_add v214, v214, v215, s[34:35] sc0
	s_mov_b64 exec, -1
	s_waitcnt vmcnt(0)
	s_nop 0
	v_readfirstlane_b32 s0, v214
	s_nop 3

; __device__ __forceinline__ unsigned xb_add(unsigned* p, unsigned v) { return __hip_atomic_fetch_add(p, v, __ATOMIC_RELAXED, __HIP_MEMORY_SCOPE_AGENT); }
; __device__ __forceinline__ void xcd_barrier(const XcdBarrier& b) {
;     asm volatile("s_waitcnt vmcnt(0)" ::: "memory");
;     __syncthreads();
;     if (threadIdx.x == 0) {
;         unsigned* bar = b.bar;
;         __builtin_amdgcn_s_waitcnt(0);
;         unsigned nloc = b.st[0], nx = b.st[1];
;         if (nloc == 0u) { xcd_barrier_complete(bar, b.x, nloc, nx); b.st[0] = nloc; b.st[1] = nx; }
;         const unsigned old = xb_add(&bar[XB_XSUB(b.x)], 1u);
.Lmy_p1d0_end:
	s_setprio 0
	s_cmp_lt_i32 s59, 6
	s_cbranch_scc1 .LBB0_628
	s_waitcnt vmcnt(0)
	s_waitcnt lgkmcnt(0)
	s_barrier
	s_and_saveexec_b64 s[0:1], s[10:11]
	s_cbranch_execz .LBB0_627
	s_add_i32 s3, 0, 0x20000
	v_mov_b32_e32 v0, s3
	s_waitcnt vmcnt(0) expcnt(0) lgkmcnt(0)
	ds_read_b32 v2, v0
	s_add_i32 s3, 0, 0x20004
	v_mov_b32_e32 v0, s3
	ds_read_b32 v0, v0
	s_waitcnt lgkmcnt(1)
	v_cmp_ne_u32_e32 vcc, 0, v2
	s_cbranch_vccnz .LBB0_591
	s_add_u32 s4, s56, 0x3fa00200
	s_addc_u32 s5, s57, 0
	s_add_u32 s6, s56, 0x3fa00400
	s_addc_u32 s7, s57, 0
	s_add_u32 s8, s56, 0x3fa00500
	s_addc_u32 s9, s57, 0
	s_add_u32 s16, s56, 0x3fa00600
	s_addc_u32 s17, s57, 0
	s_add_u32 s18, s56, 0x3fa00700
	s_addc_u32 s19, s57, 0
	s_add_u32 s20, s56, 0x3fa00800
	s_addc_u32 s21, s57, 0
	s_add_u32 s22, s56, 0x3fa00900
	s_addc_u32 s23, s57, 0
	s_add_u32 s26, s56, 0x3fa00a00
	s_addc_u32 s27, s57, 0
	s_add_u32 s28, s56, 0x3fa00b00
	s_addc_u32 s29, s57, 0
	s_add_u32 s30, s56, 0x3fa00c00
	s_addc_u32 s31, s57, 0
	s_add_u32 s38, s56, 0x3fa00d00
	s_addc_u32 s39, s57, 0
	s_add_u32 s40, s56, 0x3fa00e00
	s_addc_u32 s41, s57, 0
	s_add_u32 s44, s56, 0x3fa00f00
	s_addc_u32 s45, s57, 0
	s_add_u32 s50, s56, 0x3fa01000
	s_addc_u32 s51, s57, 0
	s_add_u32 s60, s56, 0x3fa01100
	s_addc_u32 s61, s57, 0
	s_add_u32 s64, s56, 0x3fa01200
	v_readlane_b32 s3, v255, 0
	s_addc_u32 s65, s57, 0
	s_mul_i32 s3, s97, s3
	s_add_u32 s66, s56, 0x3fa01300
	s_mul_i32 s3, s3, s96
	s_addc_u32 s67, s57, 0
	s_mov_b32 s74, 1
	v_mov_b32_e32 v16, 0
	s_branch .LBB0_579
